# v111 + stick-breaking attention: same XCD-local (batch, head) unit mapping
# baseline (speedup 1.0000x reference)
.LBB0_582:
	s_cmpk_lg_u32 s24, 0x100
	s_cbranch_scc1 .Lsb_noremap
	s_and_b32 s96, s3, 7
	s_lshl_b32 s96, s96, 2
	s_lshr_b32 s97, s3, 6
	s_add_i32 s96, s96, s97
	s_lshl_b32 s96, s96, 3
	s_bfe_u32 s97, s3, 0x30003
	s_or_b32 s3, s96, s97
